# baseline (speedup 1.0000x reference)
; __device__ __forceinline__ void phase_convert(const Params& p, u16* lds) {
;     ...
;     const long n4x = (long)NTOK * D / 4, n4m = (long)1024 * D / 4;
;     const long stride = (long)gridDim.x * blockDim.x;
;     const f32x4* xs = reinterpret_cast<const f32x4*>(p.x);
;     u32x2* xd = reinterpret_cast<u32x2*>(WSP(u16, WS_XB));
;     for (long i = (long)bid * blockDim.x + tid; i < n4x; i += stride) {
;       f32x4 v = __builtin_nontemporal_load(xs + i);
;       xd[i] = u32x2{pk2(v[0], v[1]), pk2(v[2], v[3])};
;     }
.LBB0_370:
	v_readlane_b32 s6, v248, 1
	v_readlane_b32 s7, v248, 2
	s_load_dword s0, s[6:7], 0x10
	s_load_dword s2, s[6:7], 0x0
	v_ashrrev_i32_e32 v35, 31, v34
	s_waitcnt lgkmcnt(0)
	s_lshr_b32 s0, s0, 16
	s_cmp_lg_u32 s0, 0
	s_cselect_b64 s[0:1], -1, 0
	s_cmp_lg_u64 s[0:1], 0
	s_addc_u32 s4, s2, 0
	v_readlane_b32 s0, v248, 0
	s_cmp_lt_u32 s0, s2
	s_cselect_b32 s0, 12, 18
	s_add_u32 s0, s6, s0
	s_addc_u32 s1, s7, 0
	s_nop 0
	global_load_ushort v0, v1, s[0:1]
	s_mov_b64 s[0:1], 0x800000
	s_waitcnt vmcnt(0)
	v_readfirstlane_b32 s2, v0
	v_and_b32_e32 v0, 0xffff, v0
	s_and_b32 s5, s2, 0xffff
	v_mad_i64_i32 v[4:5], s[2:3], v0, s36, v[34:35]
	v_mul_hi_u32 v3, s4, v0
	v_mul_lo_u32 v2, s4, v0
	v_cmp_gt_i64_e32 vcc, s[0:1], v[4:5]
	s_mul_hi_u32 s1, s5, s4
	s_mul_i32 s0, s5, s4
	v_lshl_add_u64 v[6:7], v[4:5], 3, s[82:83]
	s_and_saveexec_b64 s[2:3], vcc
	s_cbranch_execz .LBB0_373
	v_readlane_b32 s4, v248, 27
	v_readlane_b32 s6, v248, 29
	v_readlane_b32 s7, v248, 30
	v_readlane_b32 s5, v248, 28
	v_readlane_b32 s8, v248, 31
	v_readlane_b32 s9, v248, 32
	s_mov_b64 s[6:7], 0x19c10000
	v_lshl_add_u64 v[8:9], v[4:5], 4, s[4:5]
	s_lshl_b64 s[4:5], s[0:1], 4
	v_lshl_add_u64 v[10:11], v[6:7], 0, s[6:7]
	s_lshl_b64 s[6:7], s[0:1], 3
	s_mov_b64 s[8:9], 0
	v_mov_b64_e32 v[12:13], v[4:5]
	v_readlane_b32 s10, v248, 33
	v_readlane_b32 s11, v248, 34
	v_readlane_b32 s12, v248, 35
	v_readlane_b32 s13, v248, 36
	v_readlane_b32 s14, v248, 37
	v_readlane_b32 s15, v248, 38
	v_readlane_b32 s16, v248, 39
	v_readlane_b32 s17, v248, 40
	v_readlane_b32 s18, v248, 41
	v_readlane_b32 s19, v248, 42
	s_cmp_eq_u32 s4, 0x200000
	s_cbranch_scc0 .LBB0_372
	s_cmp_eq_u32 s5, 0
	s_cbranch_scc0 .LBB0_372
	s_mov_b32 s10, 8
.Lcvx_loop:
	global_load_dwordx4 v[14:17], v[8:9], off nt
	v_lshl_add_u64 v[46:47], v[8:9], 0, s[4:5]
	global_load_dwordx4 v[18:21], v[46:47], off nt
	v_lshl_add_u64 v[8:9], v[46:47], 0, s[4:5]
	global_load_dwordx4 v[22:25], v[8:9], off nt
	v_lshl_add_u64 v[46:47], v[8:9], 0, s[4:5]
	global_load_dwordx4 v[26:29], v[46:47], off nt
	v_lshl_add_u64 v[8:9], v[46:47], 0, s[4:5]
	global_load_dwordx4 v[30:33], v[8:9], off nt
	v_lshl_add_u64 v[46:47], v[8:9], 0, s[4:5]
	global_load_dwordx4 v[34:37], v[46:47], off nt
	v_lshl_add_u64 v[8:9], v[46:47], 0, s[4:5]
	global_load_dwordx4 v[38:41], v[8:9], off nt
	v_lshl_add_u64 v[46:47], v[8:9], 0, s[4:5]
	global_load_dwordx4 v[42:45], v[46:47], off nt
	v_lshl_add_u64 v[8:9], v[46:47], 0, s[4:5]
	s_waitcnt vmcnt(7)
	v_cvt_pk_bf16_f32 v14, v14, v15
	v_cvt_pk_bf16_f32 v15, v16, v17
	global_store_dwordx2 v[10:11], v[14:15], off
	v_lshl_add_u64 v[48:49], v[10:11], 0, s[6:7]
	s_waitcnt vmcnt(7)
	v_cvt_pk_bf16_f32 v18, v18, v19
	v_cvt_pk_bf16_f32 v19, v20, v21
	global_store_dwordx2 v[48:49], v[18:19], off
	v_lshl_add_u64 v[10:11], v[48:49], 0, s[6:7]
	s_waitcnt vmcnt(7)
	v_cvt_pk_bf16_f32 v22, v22, v23
	v_cvt_pk_bf16_f32 v23, v24, v25
	global_store_dwordx2 v[10:11], v[22:23], off
	v_lshl_add_u64 v[48:49], v[10:11], 0, s[6:7]
	s_waitcnt vmcnt(7)
	v_cvt_pk_bf16_f32 v26, v26, v27
	v_cvt_pk_bf16_f32 v27, v28, v29
	global_store_dwordx2 v[48:49], v[26:27], off
	v_lshl_add_u64 v[10:11], v[48:49], 0, s[6:7]
	s_waitcnt vmcnt(7)
	v_cvt_pk_bf16_f32 v30, v30, v31
	v_cvt_pk_bf16_f32 v31, v32, v33
	global_store_dwordx2 v[10:11], v[30:31], off
	v_lshl_add_u64 v[48:49], v[10:11], 0, s[6:7]
	s_waitcnt vmcnt(7)
	v_cvt_pk_bf16_f32 v34, v34, v35
	v_cvt_pk_bf16_f32 v35, v36, v37
	global_store_dwordx2 v[48:49], v[34:35], off
	v_lshl_add_u64 v[10:11], v[48:49], 0, s[6:7]
	s_waitcnt vmcnt(7)
	v_cvt_pk_bf16_f32 v38, v38, v39
	v_cvt_pk_bf16_f32 v39, v40, v41
	global_store_dwordx2 v[10:11], v[38:39], off
	v_lshl_add_u64 v[48:49], v[10:11], 0, s[6:7]
	s_waitcnt vmcnt(7)
	v_cvt_pk_bf16_f32 v42, v42, v43
	v_cvt_pk_bf16_f32 v43, v44, v45
	global_store_dwordx2 v[48:49], v[42:43], off
	v_lshl_add_u64 v[10:11], v[48:49], 0, s[6:7]
	s_sub_i32 s10, s10, 1
	s_cmp_lg_u32 s10, 0
	s_cbranch_scc1 .Lcvx_loop
	s_branch .LBB0_373

; __device__ __forceinline__ void phase_convert(const Params& p, u16* lds) {
;     ...
;     const f32x4* ms = reinterpret_cast<const f32x4*>(p.mem);
;     u32x2* md = reinterpret_cast<u32x2*>(WSP(u16, WS_MEMB));
;     for (long i = (long)bid * blockDim.x + tid; i < n4m; i += stride) {
;       f32x4 v = __builtin_nontemporal_load(ms + i);
;       md[i] = u32x2{pk2(v[0], v[1]), pk2(v[2], v[3])};
;     }
.LBB0_373:
	s_or_b64 exec, exec, s[2:3]
	s_mov_b64 s[2:3], 0x100000
	v_cmp_gt_i64_e32 vcc, s[2:3], v[4:5]
	s_and_saveexec_b64 s[2:3], vcc
	s_cbranch_execz .LBB0_376
	v_readlane_b32 s4, v248, 27
	v_readlane_b32 s6, v248, 29
	v_readlane_b32 s7, v248, 30
	v_readlane_b32 s5, v248, 28
	s_lshl_b64 s[4:5], s[0:1], 4
	v_lshl_add_u64 v[8:9], v[4:5], 4, s[6:7]
	s_mov_b64 s[6:7], 0x1dc10000
	v_lshl_add_u64 v[6:7], v[6:7], 0, s[6:7]
	s_lshl_b64 s[0:1], s[0:1], 3
	s_mov_b64 s[6:7], 0
	v_readlane_b32 s8, v248, 31
	v_readlane_b32 s9, v248, 32
	v_readlane_b32 s10, v248, 33
	v_readlane_b32 s11, v248, 34
	v_readlane_b32 s12, v248, 35
	v_readlane_b32 s13, v248, 36
	v_readlane_b32 s14, v248, 37
	v_readlane_b32 s15, v248, 38
	v_readlane_b32 s16, v248, 39
	v_readlane_b32 s17, v248, 40
	v_readlane_b32 s18, v248, 41
	v_readlane_b32 s19, v248, 42
	s_cmp_eq_u32 s4, 0x200000
	s_cbranch_scc0 .LBB0_375
	s_cmp_eq_u32 s5, 0
	s_cbranch_scc0 .LBB0_375
	global_load_dwordx4 v[14:17], v[8:9], off nt
	v_lshl_add_u64 v[46:47], v[8:9], 0, s[4:5]
	global_load_dwordx4 v[18:21], v[46:47], off nt
	v_lshl_add_u64 v[8:9], v[46:47], 0, s[4:5]
	global_load_dwordx4 v[22:25], v[8:9], off nt
	v_lshl_add_u64 v[46:47], v[8:9], 0, s[4:5]
	global_load_dwordx4 v[26:29], v[46:47], off nt
	v_lshl_add_u64 v[8:9], v[46:47], 0, s[4:5]
	global_load_dwordx4 v[30:33], v[8:9], off nt
	v_lshl_add_u64 v[46:47], v[8:9], 0, s[4:5]
	global_load_dwordx4 v[34:37], v[46:47], off nt
	v_lshl_add_u64 v[8:9], v[46:47], 0, s[4:5]
	global_load_dwordx4 v[38:41], v[8:9], off nt
	v_lshl_add_u64 v[46:47], v[8:9], 0, s[4:5]
	global_load_dwordx4 v[42:45], v[46:47], off nt
	v_lshl_add_u64 v[8:9], v[46:47], 0, s[4:5]
	s_waitcnt vmcnt(7)
	v_cvt_pk_bf16_f32 v14, v14, v15
	v_cvt_pk_bf16_f32 v15, v16, v17
	global_store_dwordx2 v[6:7], v[14:15], off
	v_lshl_add_u64 v[48:49], v[6:7], 0, s[0:1]
	s_waitcnt vmcnt(7)
	v_cvt_pk_bf16_f32 v18, v18, v19
	v_cvt_pk_bf16_f32 v19, v20, v21
	global_store_dwordx2 v[48:49], v[18:19], off
	v_lshl_add_u64 v[6:7], v[48:49], 0, s[0:1]
	s_waitcnt vmcnt(7)
	v_cvt_pk_bf16_f32 v22, v22, v23
	v_cvt_pk_bf16_f32 v23, v24, v25
	global_store_dwordx2 v[6:7], v[22:23], off
	v_lshl_add_u64 v[48:49], v[6:7], 0, s[0:1]
	s_waitcnt vmcnt(7)
	v_cvt_pk_bf16_f32 v26, v26, v27
	v_cvt_pk_bf16_f32 v27, v28, v29
	global_store_dwordx2 v[48:49], v[26:27], off
	v_lshl_add_u64 v[6:7], v[48:49], 0, s[0:1]
	s_waitcnt vmcnt(7)
	v_cvt_pk_bf16_f32 v30, v30, v31
	v_cvt_pk_bf16_f32 v31, v32, v33
	global_store_dwordx2 v[6:7], v[30:31], off
	v_lshl_add_u64 v[48:49], v[6:7], 0, s[0:1]
	s_waitcnt vmcnt(7)
	v_cvt_pk_bf16_f32 v34, v34, v35
	v_cvt_pk_bf16_f32 v35, v36, v37
	global_store_dwordx2 v[48:49], v[34:35], off
	v_lshl_add_u64 v[6:7], v[48:49], 0, s[0:1]
	s_waitcnt vmcnt(7)
	v_cvt_pk_bf16_f32 v38, v38, v39
	v_cvt_pk_bf16_f32 v39, v40, v41
	global_store_dwordx2 v[6:7], v[38:39], off
	v_lshl_add_u64 v[48:49], v[6:7], 0, s[0:1]
	s_waitcnt vmcnt(7)
	v_cvt_pk_bf16_f32 v42, v42, v43
	v_cvt_pk_bf16_f32 v43, v44, v45
	global_store_dwordx2 v[48:49], v[42:43], off
	v_lshl_add_u64 v[6:7], v[48:49], 0, s[0:1]
	s_branch .LBB0_376
